# next-unit tile decode in the four GEMM unit loops replaced by its closed form for these shapes (pm fixed per workgroup, pn = unit>>6): ~50 SALU + float-rcp division per unit removed
# speedup vs baseline: 1.0019x; 1.0019x over previous
;     __host__ __device__ bool next(int i, Unit& u) const { const long L = (long)i * G + c; if (L >= nwg) return false; u.pm = 0; u.pn = c % nN; return true; }
;     __host__ __device__ bool next(int i, Unit& u) const {
;         const long L = (long)i * G + c; if (L >= nwg) return false;
;         int wgid = (int)L; { const int q = nwg / NXCD, r = nwg % NXCD, xcd = wgid % NXCD, off = wgid / NXCD; wgid = (xcd < r ? xcd * (q + 1) : r * (q + 1) + (xcd - r) * q) + off; }
;         const int nig = WGM * nN, gid = wgid / nig, fm = gid * WGM, gsz = (nM - fm) < WGM ? (nM - fm) : WGM;
;         u.pm = fm + ((wgid % nig) % gsz); u.pn = (wgid % nig) / gsz; return true;
;     }
.LBB0_252:
	s_add_i32 s29, s29, 1
	s_mul_i32 s10, s29, s91
	s_mul_hi_u32 s11, s29, s90
	s_add_i32 s11, s11, s10
	s_mul_i32 s10, s29, s90
	s_add_u32 s80, s10, s2
	s_addc_u32 s81, s11, s93
	v_mov_b64_e32 v[2:3], 0x700
	v_cmp_gt_i64_e32 vcc, s[80:81], v[190:191]
	v_cmp_lt_i64_e64 s[10:11], s[80:81], v[2:3]
	s_cbranch_vccnz .LBB0_254
	s_and_b32 s13, s80, 7
	s_lshl_b32 s13, s13, 3
	s_bfe_u32 s24, s80, 0x30003
	s_or_b32 s78, s13, s24
	s_lshr_b32 s76, s80, 6

;     __host__ __device__ bool next(int i, Unit& u) const { const long L = (long)i * G + c; if (L >= nwg) return false; u.pm = 0; u.pn = c % nN; return true; }
;     __host__ __device__ bool next(int i, Unit& u) const {
;         const long L = (long)i * G + c; if (L >= nwg) return false;
;         int wgid = (int)L; { const int q = nwg / NXCD, r = nwg % NXCD, xcd = wgid % NXCD, off = wgid / NXCD; wgid = (xcd < r ? xcd * (q + 1) : r * (q + 1) + (xcd - r) * q) + off; }
;         const int nig = WGM * nN, gid = wgid / nig, fm = gid * WGM, gsz = (nM - fm) < WGM ? (nM - fm) : WGM;
;         u.pm = fm + ((wgid % nig) % gsz); u.pn = (wgid % nig) / gsz; return true;
;     }
.LBB0_765:
	s_add_i32 s72, s72, 1
	s_mul_i32 s6, s72, s68
	s_mul_hi_u32 s7, s72, s90
	s_add_i32 s7, s7, s6
	s_mul_i32 s6, s72, s90
	s_add_u32 s56, s6, s2
	s_addc_u32 s57, s7, s69
	v_cmp_gt_i64_e32 vcc, s[56:57], v[192:193]
	v_cmp_lt_i64_e64 s[6:7], s[56:57], v[190:191]
	s_cbranch_vccnz .LBB0_771
	s_and_b32 s24, s56, 7
	s_lshl_b32 s24, s24, 3
	s_bfe_u32 s25, s56, 0x30003
	s_or_b32 s54, s24, s25
	s_lshr_b32 s52, s56, 6

;     __host__ __device__ bool next(int i, Unit& u) const { const long L = (long)i * G + c; if (L >= nwg) return false; u.pm = 0; u.pn = c % nN; return true; }
;     __host__ __device__ bool next(int i, Unit& u) const {
;         const long L = (long)i * G + c; if (L >= nwg) return false;
;         int wgid = (int)L; { const int q = nwg / NXCD, r = nwg % NXCD, xcd = wgid % NXCD, off = wgid / NXCD; wgid = (xcd < r ? xcd * (q + 1) : r * (q + 1) + (xcd - r) * q) + off; }
;         const int nig = WGM * nN, gid = wgid / nig, fm = gid * WGM, gsz = (nM - fm) < WGM ? (nM - fm) : WGM;
;         u.pm = fm + ((wgid % nig) % gsz); u.pn = (wgid % nig) / gsz; return true;
;     }
.LBB0_912:
	s_add_i32 s69, s69, 1
	s_mul_i32 s4, s69, s73
	s_mul_hi_u32 s5, s69, s90
	s_add_i32 s5, s5, s4
	s_mul_i32 s4, s69, s90
	s_add_u32 s4, s4, s2
	s_addc_u32 s5, s5, s63
	v_cmp_gt_i64_e32 vcc, s[4:5], v[144:145]
	v_cmp_lt_i64_e64 s[6:7], s[4:5], v[142:143]
	s_cbranch_vccnz .LBB0_914
	s_and_b32 s5, s4, 7
	s_lshl_b32 s5, s5, 3
	s_bfe_u32 s15, s4, 0x30003
	s_or_b32 s83, s5, s15
	s_lshr_b32 s50, s4, 6

;     __host__ __device__ bool next(int i, Unit& u) const { const long L = (long)i * G + c; if (L >= nwg) return false; u.pm = 0; u.pn = c % nN; return true; }
;     __host__ __device__ bool next(int i, Unit& u) const {
;         const long L = (long)i * G + c; if (L >= nwg) return false;
;         int wgid = (int)L; { const int q = nwg / NXCD, r = nwg % NXCD, xcd = wgid % NXCD, off = wgid / NXCD; wgid = (xcd < r ? xcd * (q + 1) : r * (q + 1) + (xcd - r) * q) + off; }
;         const int nig = WGM * nN, gid = wgid / nig, fm = gid * WGM, gsz = (nM - fm) < WGM ? (nM - fm) : WGM;
;         u.pm = fm + ((wgid % nig) % gsz); u.pn = (wgid % nig) / gsz; return true;
;     }
.LBB0_989:
	s_add_i32 s27, s27, 1
	s_mul_i32 s4, s27, s58
	s_mul_hi_u32 s5, s27, s90
	s_add_i32 s5, s5, s4
	s_mul_i32 s4, s27, s90
	s_add_u32 s4, s4, s2
	s_addc_u32 s5, s5, s3
	v_cmp_gt_i64_e32 vcc, s[4:5], v[174:175]
	v_cmp_lt_i64_e64 s[6:7], s[4:5], v[172:173]
	s_cbranch_vccnz .LBB0_995
	s_and_b32 s5, s4, 7
	s_lshl_b32 s5, s5, 3
	s_bfe_u32 s24, s4, 0x30003
	s_or_b32 s62, s5, s24
	s_lshr_b32 s61, s4, 6
